# adds adaLN GEMV k-loop with 32 row loads in flight per wave (two 16-row register sets)
# speedup vs baseline: 1.0258x; 1.0040x over previous
.LBB0_52:
	s_mov_b32 s60, 0x6000
	s_mov_b32 s61, 0
	v_mov_b32_e32 v170, v40
	v_mov_b32_e32 v171, v41
	global_load_dwordx2 v[106:107], v[170:171], off
	v_lshl_add_u64 v[170:171], v[170:171], 0, s[60:61]
	global_load_dwordx2 v[108:109], v[170:171], off
	v_lshl_add_u64 v[170:171], v[170:171], 0, s[60:61]
	global_load_dwordx2 v[110:111], v[170:171], off
	v_lshl_add_u64 v[170:171], v[170:171], 0, s[60:61]
	global_load_dwordx2 v[112:113], v[170:171], off
	v_lshl_add_u64 v[170:171], v[170:171], 0, s[60:61]
	global_load_dwordx2 v[114:115], v[170:171], off
	v_lshl_add_u64 v[170:171], v[170:171], 0, s[60:61]
	global_load_dwordx2 v[116:117], v[170:171], off
	v_lshl_add_u64 v[170:171], v[170:171], 0, s[60:61]
	global_load_dwordx2 v[118:119], v[170:171], off
	v_lshl_add_u64 v[170:171], v[170:171], 0, s[60:61]
	global_load_dwordx2 v[120:121], v[170:171], off
	v_lshl_add_u64 v[170:171], v[170:171], 0, s[60:61]
	global_load_dwordx2 v[122:123], v[170:171], off
	v_lshl_add_u64 v[170:171], v[170:171], 0, s[60:61]
	global_load_dwordx2 v[124:125], v[170:171], off
	v_lshl_add_u64 v[170:171], v[170:171], 0, s[60:61]
	global_load_dwordx2 v[126:127], v[170:171], off
	v_lshl_add_u64 v[170:171], v[170:171], 0, s[60:61]
	global_load_dwordx2 v[128:129], v[170:171], off
	v_lshl_add_u64 v[170:171], v[170:171], 0, s[60:61]
	global_load_dwordx2 v[130:131], v[170:171], off
	v_lshl_add_u64 v[170:171], v[170:171], 0, s[60:61]
	global_load_dwordx2 v[132:133], v[170:171], off
	v_lshl_add_u64 v[170:171], v[170:171], 0, s[60:61]
	global_load_dwordx2 v[134:135], v[170:171], off
	v_lshl_add_u64 v[170:171], v[170:171], 0, s[60:61]
	global_load_dwordx2 v[136:137], v[170:171], off
	v_lshl_add_u64 v[170:171], v[170:171], 0, s[60:61]
	global_load_dwordx2 v[138:139], v[170:171], off
	v_lshl_add_u64 v[170:171], v[170:171], 0, s[60:61]
	global_load_dwordx2 v[140:141], v[170:171], off
	v_lshl_add_u64 v[170:171], v[170:171], 0, s[60:61]
	global_load_dwordx2 v[142:143], v[170:171], off
	v_lshl_add_u64 v[170:171], v[170:171], 0, s[60:61]
	global_load_dwordx2 v[144:145], v[170:171], off
	v_lshl_add_u64 v[170:171], v[170:171], 0, s[60:61]
	global_load_dwordx2 v[146:147], v[170:171], off
	v_lshl_add_u64 v[170:171], v[170:171], 0, s[60:61]
	global_load_dwordx2 v[148:149], v[170:171], off
	v_lshl_add_u64 v[170:171], v[170:171], 0, s[60:61]
	global_load_dwordx2 v[150:151], v[170:171], off
	v_lshl_add_u64 v[170:171], v[170:171], 0, s[60:61]
	global_load_dwordx2 v[152:153], v[170:171], off
	v_lshl_add_u64 v[170:171], v[170:171], 0, s[60:61]
	global_load_dwordx2 v[154:155], v[170:171], off
	v_lshl_add_u64 v[170:171], v[170:171], 0, s[60:61]
	global_load_dwordx2 v[156:157], v[170:171], off
	v_lshl_add_u64 v[170:171], v[170:171], 0, s[60:61]
	global_load_dwordx2 v[158:159], v[170:171], off
	v_lshl_add_u64 v[170:171], v[170:171], 0, s[60:61]
	global_load_dwordx2 v[160:161], v[170:171], off
	v_lshl_add_u64 v[170:171], v[170:171], 0, s[60:61]
	global_load_dwordx2 v[162:163], v[170:171], off
	v_lshl_add_u64 v[170:171], v[170:171], 0, s[60:61]
	global_load_dwordx2 v[164:165], v[170:171], off
	v_lshl_add_u64 v[170:171], v[170:171], 0, s[60:61]
	global_load_dwordx2 v[166:167], v[170:171], off
	v_lshl_add_u64 v[170:171], v[170:171], 0, s[60:61]
	global_load_dwordx2 v[168:169], v[170:171], off
	v_lshl_add_u64 v[170:171], v[170:171], 0, s[60:61]
	s_mov_b32 s62, 0
.Lada_loop:
	s_waitcnt vmcnt(16)
	ds_read_b128 v[72:75], v4 offset:0
	ds_read_b128 v[76:79], v4 offset:4096
	ds_read_b128 v[80:83], v4 offset:8192
	ds_read_b128 v[84:87], v4 offset:12288
	ds_read_b128 v[88:91], v4 offset:16384
	s_waitcnt lgkmcnt(0)
	v_pk_fma_f32 v[44:45], v[106:107], v[72:73], v[44:45] op_sel_hi:[1,0,1]
	v_pk_fma_f32 v[46:47], v[106:107], v[76:77], v[46:47] op_sel_hi:[1,0,1]
	v_pk_fma_f32 v[48:49], v[106:107], v[80:81], v[48:49] op_sel_hi:[1,0,1]
	v_pk_fma_f32 v[50:51], v[106:107], v[84:85], v[50:51] op_sel_hi:[1,0,1]
	v_pk_fma_f32 v[42:43], v[106:107], v[88:89], v[42:43] op_sel_hi:[1,0,1]
	v_pk_fma_f32 v[44:45], v[108:109], v[72:73], v[44:45] op_sel:[0,1,0]
	v_pk_fma_f32 v[46:47], v[108:109], v[76:77], v[46:47] op_sel:[0,1,0]
	v_pk_fma_f32 v[48:49], v[108:109], v[80:81], v[48:49] op_sel:[0,1,0]
	v_pk_fma_f32 v[50:51], v[108:109], v[84:85], v[50:51] op_sel:[0,1,0]
	v_pk_fma_f32 v[42:43], v[108:109], v[88:89], v[42:43] op_sel:[0,1,0]
	v_pk_fma_f32 v[44:45], v[110:111], v[74:75], v[44:45] op_sel_hi:[1,0,1]
	v_pk_fma_f32 v[46:47], v[110:111], v[78:79], v[46:47] op_sel_hi:[1,0,1]
	v_pk_fma_f32 v[48:49], v[110:111], v[82:83], v[48:49] op_sel_hi:[1,0,1]
	v_pk_fma_f32 v[50:51], v[110:111], v[86:87], v[50:51] op_sel_hi:[1,0,1]
	v_pk_fma_f32 v[42:43], v[110:111], v[90:91], v[42:43] op_sel_hi:[1,0,1]
	v_pk_fma_f32 v[44:45], v[112:113], v[74:75], v[44:45] op_sel:[0,1,0]
	v_pk_fma_f32 v[46:47], v[112:113], v[78:79], v[46:47] op_sel:[0,1,0]
	v_pk_fma_f32 v[48:49], v[112:113], v[82:83], v[48:49] op_sel:[0,1,0]
	v_pk_fma_f32 v[50:51], v[112:113], v[86:87], v[50:51] op_sel:[0,1,0]
	v_pk_fma_f32 v[42:43], v[112:113], v[90:91], v[42:43] op_sel:[0,1,0]
	ds_read_b128 v[72:75], v4 offset:16
	ds_read_b128 v[76:79], v4 offset:4112
	ds_read_b128 v[80:83], v4 offset:8208
	ds_read_b128 v[84:87], v4 offset:12304
	ds_read_b128 v[88:91], v4 offset:16400
	s_waitcnt lgkmcnt(0)
	v_pk_fma_f32 v[44:45], v[114:115], v[72:73], v[44:45] op_sel_hi:[1,0,1]
	v_pk_fma_f32 v[46:47], v[114:115], v[76:77], v[46:47] op_sel_hi:[1,0,1]
	v_pk_fma_f32 v[48:49], v[114:115], v[80:81], v[48:49] op_sel_hi:[1,0,1]
	v_pk_fma_f32 v[50:51], v[114:115], v[84:85], v[50:51] op_sel_hi:[1,0,1]
	v_pk_fma_f32 v[42:43], v[114:115], v[88:89], v[42:43] op_sel_hi:[1,0,1]
	v_pk_fma_f32 v[44:45], v[116:117], v[72:73], v[44:45] op_sel:[0,1,0]
	v_pk_fma_f32 v[46:47], v[116:117], v[76:77], v[46:47] op_sel:[0,1,0]
	v_pk_fma_f32 v[48:49], v[116:117], v[80:81], v[48:49] op_sel:[0,1,0]
	v_pk_fma_f32 v[50:51], v[116:117], v[84:85], v[50:51] op_sel:[0,1,0]
	v_pk_fma_f32 v[42:43], v[116:117], v[88:89], v[42:43] op_sel:[0,1,0]
	v_pk_fma_f32 v[44:45], v[118:119], v[74:75], v[44:45] op_sel_hi:[1,0,1]
	v_pk_fma_f32 v[46:47], v[118:119], v[78:79], v[46:47] op_sel_hi:[1,0,1]
	v_pk_fma_f32 v[48:49], v[118:119], v[82:83], v[48:49] op_sel_hi:[1,0,1]
	v_pk_fma_f32 v[50:51], v[118:119], v[86:87], v[50:51] op_sel_hi:[1,0,1]
	v_pk_fma_f32 v[42:43], v[118:119], v[90:91], v[42:43] op_sel_hi:[1,0,1]
	v_pk_fma_f32 v[44:45], v[120:121], v[74:75], v[44:45] op_sel:[0,1,0]
	v_pk_fma_f32 v[46:47], v[120:121], v[78:79], v[46:47] op_sel:[0,1,0]
	v_pk_fma_f32 v[48:49], v[120:121], v[82:83], v[48:49] op_sel:[0,1,0]
	v_pk_fma_f32 v[50:51], v[120:121], v[86:87], v[50:51] op_sel:[0,1,0]
	v_pk_fma_f32 v[42:43], v[120:121], v[90:91], v[42:43] op_sel:[0,1,0]
	ds_read_b128 v[72:75], v4 offset:32
	ds_read_b128 v[76:79], v4 offset:4128
	ds_read_b128 v[80:83], v4 offset:8224
	ds_read_b128 v[84:87], v4 offset:12320
	ds_read_b128 v[88:91], v4 offset:16416
	s_waitcnt lgkmcnt(0)
	v_pk_fma_f32 v[44:45], v[122:123], v[72:73], v[44:45] op_sel_hi:[1,0,1]
	v_pk_fma_f32 v[46:47], v[122:123], v[76:77], v[46:47] op_sel_hi:[1,0,1]
	v_pk_fma_f32 v[48:49], v[122:123], v[80:81], v[48:49] op_sel_hi:[1,0,1]
	v_pk_fma_f32 v[50:51], v[122:123], v[84:85], v[50:51] op_sel_hi:[1,0,1]
	v_pk_fma_f32 v[42:43], v[122:123], v[88:89], v[42:43] op_sel_hi:[1,0,1]
	v_pk_fma_f32 v[44:45], v[124:125], v[72:73], v[44:45] op_sel:[0,1,0]
	v_pk_fma_f32 v[46:47], v[124:125], v[76:77], v[46:47] op_sel:[0,1,0]
	v_pk_fma_f32 v[48:49], v[124:125], v[80:81], v[48:49] op_sel:[0,1,0]
	v_pk_fma_f32 v[50:51], v[124:125], v[84:85], v[50:51] op_sel:[0,1,0]
	v_pk_fma_f32 v[42:43], v[124:125], v[88:89], v[42:43] op_sel:[0,1,0]
	v_pk_fma_f32 v[44:45], v[126:127], v[74:75], v[44:45] op_sel_hi:[1,0,1]
	v_pk_fma_f32 v[46:47], v[126:127], v[78:79], v[46:47] op_sel_hi:[1,0,1]
	v_pk_fma_f32 v[48:49], v[126:127], v[82:83], v[48:49] op_sel_hi:[1,0,1]
	v_pk_fma_f32 v[50:51], v[126:127], v[86:87], v[50:51] op_sel_hi:[1,0,1]
	v_pk_fma_f32 v[42:43], v[126:127], v[90:91], v[42:43] op_sel_hi:[1,0,1]
	v_pk_fma_f32 v[44:45], v[128:129], v[74:75], v[44:45] op_sel:[0,1,0]
	v_pk_fma_f32 v[46:47], v[128:129], v[78:79], v[46:47] op_sel:[0,1,0]
	v_pk_fma_f32 v[48:49], v[128:129], v[82:83], v[48:49] op_sel:[0,1,0]
	v_pk_fma_f32 v[50:51], v[128:129], v[86:87], v[50:51] op_sel:[0,1,0]
	v_pk_fma_f32 v[42:43], v[128:129], v[90:91], v[42:43] op_sel:[0,1,0]
	ds_read_b128 v[72:75], v4 offset:48
	ds_read_b128 v[76:79], v4 offset:4144
	ds_read_b128 v[80:83], v4 offset:8240
	ds_read_b128 v[84:87], v4 offset:12336
	ds_read_b128 v[88:91], v4 offset:16432
	s_waitcnt lgkmcnt(0)
	v_pk_fma_f32 v[44:45], v[130:131], v[72:73], v[44:45] op_sel_hi:[1,0,1]
	v_pk_fma_f32 v[46:47], v[130:131], v[76:77], v[46:47] op_sel_hi:[1,0,1]
	v_pk_fma_f32 v[48:49], v[130:131], v[80:81], v[48:49] op_sel_hi:[1,0,1]
	v_pk_fma_f32 v[50:51], v[130:131], v[84:85], v[50:51] op_sel_hi:[1,0,1]
	v_pk_fma_f32 v[42:43], v[130:131], v[88:89], v[42:43] op_sel_hi:[1,0,1]
	v_pk_fma_f32 v[44:45], v[132:133], v[72:73], v[44:45] op_sel:[0,1,0]
	v_pk_fma_f32 v[46:47], v[132:133], v[76:77], v[46:47] op_sel:[0,1,0]
	v_pk_fma_f32 v[48:49], v[132:133], v[80:81], v[48:49] op_sel:[0,1,0]
	v_pk_fma_f32 v[50:51], v[132:133], v[84:85], v[50:51] op_sel:[0,1,0]
	v_pk_fma_f32 v[42:43], v[132:133], v[88:89], v[42:43] op_sel:[0,1,0]
	v_pk_fma_f32 v[44:45], v[134:135], v[74:75], v[44:45] op_sel_hi:[1,0,1]
	v_pk_fma_f32 v[46:47], v[134:135], v[78:79], v[46:47] op_sel_hi:[1,0,1]
	v_pk_fma_f32 v[48:49], v[134:135], v[82:83], v[48:49] op_sel_hi:[1,0,1]
	v_pk_fma_f32 v[50:51], v[134:135], v[86:87], v[50:51] op_sel_hi:[1,0,1]
	v_pk_fma_f32 v[42:43], v[134:135], v[90:91], v[42:43] op_sel_hi:[1,0,1]
	v_pk_fma_f32 v[44:45], v[136:137], v[74:75], v[44:45] op_sel:[0,1,0]
	v_pk_fma_f32 v[46:47], v[136:137], v[78:79], v[46:47] op_sel:[0,1,0]
	v_pk_fma_f32 v[48:49], v[136:137], v[82:83], v[48:49] op_sel:[0,1,0]
	v_pk_fma_f32 v[50:51], v[136:137], v[86:87], v[50:51] op_sel:[0,1,0]
	v_pk_fma_f32 v[42:43], v[136:137], v[90:91], v[42:43] op_sel:[0,1,0]
	v_add_u32_e32 v4, 64, v4
	s_cmp_lt_u32 s62, 6
	s_cbranch_scc0 .Lada_nofill0
	global_load_dwordx2 v[106:107], v[170:171], off
	v_lshl_add_u64 v[170:171], v[170:171], 0, s[60:61]
	global_load_dwordx2 v[108:109], v[170:171], off
	v_lshl_add_u64 v[170:171], v[170:171], 0, s[60:61]
	global_load_dwordx2 v[110:111], v[170:171], off
	v_lshl_add_u64 v[170:171], v[170:171], 0, s[60:61]
	global_load_dwordx2 v[112:113], v[170:171], off
	v_lshl_add_u64 v[170:171], v[170:171], 0, s[60:61]
	global_load_dwordx2 v[114:115], v[170:171], off
	v_lshl_add_u64 v[170:171], v[170:171], 0, s[60:61]
	global_load_dwordx2 v[116:117], v[170:171], off
	v_lshl_add_u64 v[170:171], v[170:171], 0, s[60:61]
	global_load_dwordx2 v[118:119], v[170:171], off
	v_lshl_add_u64 v[170:171], v[170:171], 0, s[60:61]
	global_load_dwordx2 v[120:121], v[170:171], off
	v_lshl_add_u64 v[170:171], v[170:171], 0, s[60:61]
	global_load_dwordx2 v[122:123], v[170:171], off
	v_lshl_add_u64 v[170:171], v[170:171], 0, s[60:61]
	global_load_dwordx2 v[124:125], v[170:171], off
	v_lshl_add_u64 v[170:171], v[170:171], 0, s[60:61]
	global_load_dwordx2 v[126:127], v[170:171], off
	v_lshl_add_u64 v[170:171], v[170:171], 0, s[60:61]
	global_load_dwordx2 v[128:129], v[170:171], off
	v_lshl_add_u64 v[170:171], v[170:171], 0, s[60:61]
	global_load_dwordx2 v[130:131], v[170:171], off
	v_lshl_add_u64 v[170:171], v[170:171], 0, s[60:61]
	global_load_dwordx2 v[132:133], v[170:171], off
	v_lshl_add_u64 v[170:171], v[170:171], 0, s[60:61]
	global_load_dwordx2 v[134:135], v[170:171], off
	v_lshl_add_u64 v[170:171], v[170:171], 0, s[60:61]
	global_load_dwordx2 v[136:137], v[170:171], off
	v_lshl_add_u64 v[170:171], v[170:171], 0, s[60:61]
.Lada_nofill0:
	s_add_u32 s62, s62, 1
	s_cmp_lt_u32 s62, 7
	s_cbranch_scc1 .Lada_w16
	s_waitcnt vmcnt(0)
	s_branch .Lada_go
.Lada_w16:
	s_waitcnt vmcnt(16)
.Lada_go:
	ds_read_b128 v[72:75], v4 offset:0
	ds_read_b128 v[76:79], v4 offset:4096
	ds_read_b128 v[80:83], v4 offset:8192
	ds_read_b128 v[84:87], v4 offset:12288
	ds_read_b128 v[88:91], v4 offset:16384
	s_waitcnt lgkmcnt(0)
	v_pk_fma_f32 v[44:45], v[138:139], v[72:73], v[44:45] op_sel_hi:[1,0,1]
	v_pk_fma_f32 v[46:47], v[138:139], v[76:77], v[46:47] op_sel_hi:[1,0,1]
	v_pk_fma_f32 v[48:49], v[138:139], v[80:81], v[48:49] op_sel_hi:[1,0,1]
	v_pk_fma_f32 v[50:51], v[138:139], v[84:85], v[50:51] op_sel_hi:[1,0,1]
	v_pk_fma_f32 v[42:43], v[138:139], v[88:89], v[42:43] op_sel_hi:[1,0,1]
	v_pk_fma_f32 v[44:45], v[140:141], v[72:73], v[44:45] op_sel:[0,1,0]
	v_pk_fma_f32 v[46:47], v[140:141], v[76:77], v[46:47] op_sel:[0,1,0]
	v_pk_fma_f32 v[48:49], v[140:141], v[80:81], v[48:49] op_sel:[0,1,0]
	v_pk_fma_f32 v[50:51], v[140:141], v[84:85], v[50:51] op_sel:[0,1,0]
	v_pk_fma_f32 v[42:43], v[140:141], v[88:89], v[42:43] op_sel:[0,1,0]
	v_pk_fma_f32 v[44:45], v[142:143], v[74:75], v[44:45] op_sel_hi:[1,0,1]
	v_pk_fma_f32 v[46:47], v[142:143], v[78:79], v[46:47] op_sel_hi:[1,0,1]
	v_pk_fma_f32 v[48:49], v[142:143], v[82:83], v[48:49] op_sel_hi:[1,0,1]
	v_pk_fma_f32 v[50:51], v[142:143], v[86:87], v[50:51] op_sel_hi:[1,0,1]
	v_pk_fma_f32 v[42:43], v[142:143], v[90:91], v[42:43] op_sel_hi:[1,0,1]
	v_pk_fma_f32 v[44:45], v[144:145], v[74:75], v[44:45] op_sel:[0,1,0]
	v_pk_fma_f32 v[46:47], v[144:145], v[78:79], v[46:47] op_sel:[0,1,0]
	v_pk_fma_f32 v[48:49], v[144:145], v[82:83], v[48:49] op_sel:[0,1,0]
	v_pk_fma_f32 v[50:51], v[144:145], v[86:87], v[50:51] op_sel:[0,1,0]
	v_pk_fma_f32 v[42:43], v[144:145], v[90:91], v[42:43] op_sel:[0,1,0]
	ds_read_b128 v[72:75], v4 offset:16
	ds_read_b128 v[76:79], v4 offset:4112
	ds_read_b128 v[80:83], v4 offset:8208
	ds_read_b128 v[84:87], v4 offset:12304
	ds_read_b128 v[88:91], v4 offset:16400
	s_waitcnt lgkmcnt(0)
	v_pk_fma_f32 v[44:45], v[146:147], v[72:73], v[44:45] op_sel_hi:[1,0,1]
	v_pk_fma_f32 v[46:47], v[146:147], v[76:77], v[46:47] op_sel_hi:[1,0,1]
	v_pk_fma_f32 v[48:49], v[146:147], v[80:81], v[48:49] op_sel_hi:[1,0,1]
	v_pk_fma_f32 v[50:51], v[146:147], v[84:85], v[50:51] op_sel_hi:[1,0,1]
	v_pk_fma_f32 v[42:43], v[146:147], v[88:89], v[42:43] op_sel_hi:[1,0,1]
	v_pk_fma_f32 v[44:45], v[148:149], v[72:73], v[44:45] op_sel:[0,1,0]
	v_pk_fma_f32 v[46:47], v[148:149], v[76:77], v[46:47] op_sel:[0,1,0]
	v_pk_fma_f32 v[48:49], v[148:149], v[80:81], v[48:49] op_sel:[0,1,0]
	v_pk_fma_f32 v[50:51], v[148:149], v[84:85], v[50:51] op_sel:[0,1,0]
	v_pk_fma_f32 v[42:43], v[148:149], v[88:89], v[42:43] op_sel:[0,1,0]
	v_pk_fma_f32 v[44:45], v[150:151], v[74:75], v[44:45] op_sel_hi:[1,0,1]
	v_pk_fma_f32 v[46:47], v[150:151], v[78:79], v[46:47] op_sel_hi:[1,0,1]
	v_pk_fma_f32 v[48:49], v[150:151], v[82:83], v[48:49] op_sel_hi:[1,0,1]
	v_pk_fma_f32 v[50:51], v[150:151], v[86:87], v[50:51] op_sel_hi:[1,0,1]
	v_pk_fma_f32 v[42:43], v[150:151], v[90:91], v[42:43] op_sel_hi:[1,0,1]
	v_pk_fma_f32 v[44:45], v[152:153], v[74:75], v[44:45] op_sel:[0,1,0]
	v_pk_fma_f32 v[46:47], v[152:153], v[78:79], v[46:47] op_sel:[0,1,0]
	v_pk_fma_f32 v[48:49], v[152:153], v[82:83], v[48:49] op_sel:[0,1,0]
	v_pk_fma_f32 v[50:51], v[152:153], v[86:87], v[50:51] op_sel:[0,1,0]
	v_pk_fma_f32 v[42:43], v[152:153], v[90:91], v[42:43] op_sel:[0,1,0]
	ds_read_b128 v[72:75], v4 offset:32
	ds_read_b128 v[76:79], v4 offset:4128
	ds_read_b128 v[80:83], v4 offset:8224
	ds_read_b128 v[84:87], v4 offset:12320
	ds_read_b128 v[88:91], v4 offset:16416
	s_waitcnt lgkmcnt(0)
	v_pk_fma_f32 v[44:45], v[154:155], v[72:73], v[44:45] op_sel_hi:[1,0,1]
	v_pk_fma_f32 v[46:47], v[154:155], v[76:77], v[46:47] op_sel_hi:[1,0,1]
	v_pk_fma_f32 v[48:49], v[154:155], v[80:81], v[48:49] op_sel_hi:[1,0,1]
	v_pk_fma_f32 v[50:51], v[154:155], v[84:85], v[50:51] op_sel_hi:[1,0,1]
	v_pk_fma_f32 v[42:43], v[154:155], v[88:89], v[42:43] op_sel_hi:[1,0,1]
	v_pk_fma_f32 v[44:45], v[156:157], v[72:73], v[44:45] op_sel:[0,1,0]
	v_pk_fma_f32 v[46:47], v[156:157], v[76:77], v[46:47] op_sel:[0,1,0]
	v_pk_fma_f32 v[48:49], v[156:157], v[80:81], v[48:49] op_sel:[0,1,0]
	v_pk_fma_f32 v[50:51], v[156:157], v[84:85], v[50:51] op_sel:[0,1,0]
	v_pk_fma_f32 v[42:43], v[156:157], v[88:89], v[42:43] op_sel:[0,1,0]
	v_pk_fma_f32 v[44:45], v[158:159], v[74:75], v[44:45] op_sel_hi:[1,0,1]
	v_pk_fma_f32 v[46:47], v[158:159], v[78:79], v[46:47] op_sel_hi:[1,0,1]
	v_pk_fma_f32 v[48:49], v[158:159], v[82:83], v[48:49] op_sel_hi:[1,0,1]
	v_pk_fma_f32 v[50:51], v[158:159], v[86:87], v[50:51] op_sel_hi:[1,0,1]
	v_pk_fma_f32 v[42:43], v[158:159], v[90:91], v[42:43] op_sel_hi:[1,0,1]
	v_pk_fma_f32 v[44:45], v[160:161], v[74:75], v[44:45] op_sel:[0,1,0]
	v_pk_fma_f32 v[46:47], v[160:161], v[78:79], v[46:47] op_sel:[0,1,0]
	v_pk_fma_f32 v[48:49], v[160:161], v[82:83], v[48:49] op_sel:[0,1,0]
	v_pk_fma_f32 v[50:51], v[160:161], v[86:87], v[50:51] op_sel:[0,1,0]
	v_pk_fma_f32 v[42:43], v[160:161], v[90:91], v[42:43] op_sel:[0,1,0]
	ds_read_b128 v[72:75], v4 offset:48
	ds_read_b128 v[76:79], v4 offset:4144
	ds_read_b128 v[80:83], v4 offset:8240
	ds_read_b128 v[84:87], v4 offset:12336
	ds_read_b128 v[88:91], v4 offset:16432
	s_waitcnt lgkmcnt(0)
	v_pk_fma_f32 v[44:45], v[162:163], v[72:73], v[44:45] op_sel_hi:[1,0,1]
	v_pk_fma_f32 v[46:47], v[162:163], v[76:77], v[46:47] op_sel_hi:[1,0,1]
	v_pk_fma_f32 v[48:49], v[162:163], v[80:81], v[48:49] op_sel_hi:[1,0,1]
	v_pk_fma_f32 v[50:51], v[162:163], v[84:85], v[50:51] op_sel_hi:[1,0,1]
	v_pk_fma_f32 v[42:43], v[162:163], v[88:89], v[42:43] op_sel_hi:[1,0,1]
	v_pk_fma_f32 v[44:45], v[164:165], v[72:73], v[44:45] op_sel:[0,1,0]
	v_pk_fma_f32 v[46:47], v[164:165], v[76:77], v[46:47] op_sel:[0,1,0]
	v_pk_fma_f32 v[48:49], v[164:165], v[80:81], v[48:49] op_sel:[0,1,0]
	v_pk_fma_f32 v[50:51], v[164:165], v[84:85], v[50:51] op_sel:[0,1,0]
	v_pk_fma_f32 v[42:43], v[164:165], v[88:89], v[42:43] op_sel:[0,1,0]
	v_pk_fma_f32 v[44:45], v[166:167], v[74:75], v[44:45] op_sel_hi:[1,0,1]
	v_pk_fma_f32 v[46:47], v[166:167], v[78:79], v[46:47] op_sel_hi:[1,0,1]
	v_pk_fma_f32 v[48:49], v[166:167], v[82:83], v[48:49] op_sel_hi:[1,0,1]
	v_pk_fma_f32 v[50:51], v[166:167], v[86:87], v[50:51] op_sel_hi:[1,0,1]
	v_pk_fma_f32 v[42:43], v[166:167], v[90:91], v[42:43] op_sel_hi:[1,0,1]
	v_pk_fma_f32 v[44:45], v[168:169], v[74:75], v[44:45] op_sel:[0,1,0]
	v_pk_fma_f32 v[46:47], v[168:169], v[78:79], v[46:47] op_sel:[0,1,0]
	v_pk_fma_f32 v[48:49], v[168:169], v[82:83], v[48:49] op_sel:[0,1,0]
	v_pk_fma_f32 v[50:51], v[168:169], v[86:87], v[50:51] op_sel:[0,1,0]
	v_pk_fma_f32 v[42:43], v[168:169], v[90:91], v[42:43] op_sel:[0,1,0]
	v_add_u32_e32 v4, 64, v4
	s_cmp_lt_u32 s62, 6
	s_cbranch_scc0 .Lada_nofill1
	global_load_dwordx2 v[138:139], v[170:171], off
	v_lshl_add_u64 v[170:171], v[170:171], 0, s[60:61]
	global_load_dwordx2 v[140:141], v[170:171], off
	v_lshl_add_u64 v[170:171], v[170:171], 0, s[60:61]
	global_load_dwordx2 v[142:143], v[170:171], off
	v_lshl_add_u64 v[170:171], v[170:171], 0, s[60:61]
	global_load_dwordx2 v[144:145], v[170:171], off
	v_lshl_add_u64 v[170:171], v[170:171], 0, s[60:61]
	global_load_dwordx2 v[146:147], v[170:171], off
	v_lshl_add_u64 v[170:171], v[170:171], 0, s[60:61]
	global_load_dwordx2 v[148:149], v[170:171], off
	v_lshl_add_u64 v[170:171], v[170:171], 0, s[60:61]
	global_load_dwordx2 v[150:151], v[170:171], off
	v_lshl_add_u64 v[170:171], v[170:171], 0, s[60:61]
	global_load_dwordx2 v[152:153], v[170:171], off
	v_lshl_add_u64 v[170:171], v[170:171], 0, s[60:61]
	global_load_dwordx2 v[154:155], v[170:171], off
	v_lshl_add_u64 v[170:171], v[170:171], 0, s[60:61]
	global_load_dwordx2 v[156:157], v[170:171], off
	v_lshl_add_u64 v[170:171], v[170:171], 0, s[60:61]
	global_load_dwordx2 v[158:159], v[170:171], off
	v_lshl_add_u64 v[170:171], v[170:171], 0, s[60:61]
	global_load_dwordx2 v[160:161], v[170:171], off
	v_lshl_add_u64 v[170:171], v[170:171], 0, s[60:61]
	global_load_dwordx2 v[162:163], v[170:171], off
	v_lshl_add_u64 v[170:171], v[170:171], 0, s[60:61]
	global_load_dwordx2 v[164:165], v[170:171], off
	v_lshl_add_u64 v[170:171], v[170:171], 0, s[60:61]
	global_load_dwordx2 v[166:167], v[170:171], off
	v_lshl_add_u64 v[170:171], v[170:171], 0, s[60:61]
	global_load_dwordx2 v[168:169], v[170:171], off
	v_lshl_add_u64 v[170:171], v[170:171], 0, s[60:61]
.Lada_nofill1:
	s_add_u32 s62, s62, 1
	s_cmp_lt_u32 s62, 8
	s_cbranch_scc1 .Lada_loop
	ds_write2st64_b64 v70, v[44:45], v[46:47] offset0:40 offset1:41
	ds_write2st64_b64 v70, v[48:49], v[50:51] offset0:42 offset1:43
	ds_write_b64 v70, v[42:43] offset:22528
	s_waitcnt lgkmcnt(0)
	s_barrier
	s_and_saveexec_b64 s[18:19], s[8:9]
	s_cbranch_execz .LBB0_56
	s_mul_i32 s41, s40, 0x1800
	s_add_i32 s41, s41, s16
	v_or_b32_e32 v40, s41, v69
	s_mul_i32 s40, s40, 5
	v_ashrrev_i32_e32 v41, 31, v40
	v_lshl_add_u64 v[42:43], s[16:17], 2, v[14:15]
	s_mov_b64 s[16:17], 0
	v_mov_b32_e32 v4, v2
